# NSA compressed-branch loop: importance accumulation via DPP row_ror + v_permlane16_swap instead of ds_bpermute, LDS RMW by ds_add_f32, dependent LDS waits removed; P.V/Q.K fragment reads ring-buffered
# speedup vs baseline: 1.0532x; 1.0011x over previous
; #define LAS __attribute__((address_space(3)))
; __device__ __forceinline__ float fast_exp2(float x) { return __builtin_amdgcn_exp2f(x); }
; template <int DQK, bool STATS, bool PRE, class Src, class Mask, class Post> ...
;     ...
;             for (int j = 0; j < 16; ++j) { s0[j] = fast_exp2(__builtin_fmaf(s0[j], sc, -msub)); s1[j] = fast_exp2(__builtin_fmaf(s1[j], sc, -msub)); }
;     __device__ __forceinline__ void operator()(int t, const f32x16& s0, const f32x16& s1) const {
;         float Bv[8];
;         LAS float* row = impw + (c & 7) * 256;
;         asm volatile("s_waitcnt lgkmcnt(0)" ::: "memory");
; #pragma unroll
;         for (int kb = 0; kb < 2; ++kb)
; #pragma unroll
;             for (int gi = 0; gi < 4; ++gi) {
;                 float p3 = (kb ? s1[4 * gi + 3] : s0[4 * gi + 3]);
;                 float aa = kb ? (s1[4 * gi] + s1[4 * gi + 1] + s1[4 * gi + 2] + p3) : (s0[4 * gi] + s0[4 * gi + 1] + s0[4 * gi + 2] + p3);
;                 aa *= inv_l; p3 *= inv_l;
;                 aa += __shfl_xor(aa, 8); aa += __shfl_xor(aa, 16); p3 += __shfl_xor(p3, 8); p3 += __shfl_xor(p3, 16);
;                 Bv[kb * 4 + gi] = p3;
;                 if (c < 8) { const int j = t * 16 + kb * 8 + 2 * gi + h; row[j] += aa; }
;             }
;         asm volatile("s_waitcnt lgkmcnt(0)" ::: "memory");
;         if (c < 8) {
; #pragma unroll
;             for (int e = 0; e < 8; ++e) { const int j1 = t * 16 + (e >> 2) * 8 + 2 * (e & 3) + h + 1; if (j1 < 256) row[j1] += Bv[e]; }
.LBB0_882:
	v_fma_f32 v0, v16, s63, -v190
	v_exp_f32_e32 v16, v0
	v_fma_f32 v0, v17, s63, -v190
	v_exp_f32_e32 v17, v0
	v_fma_f32 v0, v18, s63, -v190
	v_exp_f32_e32 v18, v0
	v_fma_f32 v0, v19, s63, -v190
	v_exp_f32_e32 v19, v0
	v_add_f32_e32 v0, v16, v17
	v_add_f32_e32 v0, v18, v0
	s_waitcnt lgkmcnt(0)
	v_add_f32_e32 v0, v19, v0
	v_mul_f32_e32 v2, v194, v0
	s_nop 1
	v_mov_b32_dpp v4, v2 row_ror:8 row_mask:0xf bank_mask:0xf
	v_mul_f32_e32 v2, v194, v19
	s_nop 1
	v_mov_b32_dpp v2, v2 row_ror:8 row_mask:0xf bank_mask:0xf
	v_fmac_f32_e32 v4, v194, v0
	v_mov_b32_e32 v5, v4
	s_nop 1
	v_permlane16_swap_b32_e32 v5, v4
	v_fmac_f32_e32 v2, v194, v19
	v_mov_b32_e32 v3, v2
	s_nop 1
	v_permlane16_swap_b32_e32 v3, v2
	v_add_u32_e32 v0, s92, v182
	s_and_saveexec_b64 s[86:87], s[8:9]
	s_cbranch_execz .LBB0_884
	v_add_u32_e32 v6, 0x11800, v0
	v_add_f32_e32 v4, v4, v5
	ds_add_f32 v6, v4
.LBB0_884:
	s_or_b64 exec, exec, s[86:87]
	v_fma_f32 v4, v20, s63, -v190
	v_exp_f32_e32 v20, v4
	v_fma_f32 v4, v21, s63, -v190
	v_exp_f32_e32 v21, v4
	v_fma_f32 v4, v22, s63, -v190
	v_exp_f32_e32 v22, v4
	v_fma_f32 v4, v23, s63, -v190
	v_exp_f32_e32 v23, v4
	v_add_f32_e32 v4, v20, v21
	v_add_f32_e32 v4, v22, v4
	v_add_f32_e32 v5, v23, v4
	v_mul_f32_e32 v4, v194, v5
	s_nop 1
	v_mov_b32_dpp v6, v4 row_ror:8 row_mask:0xf bank_mask:0xf
	v_mul_f32_e32 v4, v194, v23
	s_nop 1
	v_mov_b32_dpp v4, v4 row_ror:8 row_mask:0xf bank_mask:0xf
	v_fmac_f32_e32 v6, v194, v5
	v_mov_b32_e32 v7, v6
	s_nop 1
	v_permlane16_swap_b32_e32 v7, v6
	v_fmac_f32_e32 v4, v194, v23
	v_mov_b32_e32 v5, v4
	s_nop 1
	v_permlane16_swap_b32_e32 v5, v4
	s_and_saveexec_b64 s[86:87], s[8:9]
	s_cbranch_execz .LBB0_886
	v_add_f32_e32 v6, v6, v7
	v_add_u32_e32 v7, 0x11808, v0
	ds_add_f32 v7, v6
.LBB0_886:
	s_or_b64 exec, exec, s[86:87]
	v_fma_f32 v6, v24, s63, -v190
	v_exp_f32_e32 v24, v6
	v_fma_f32 v6, v25, s63, -v190
	v_exp_f32_e32 v25, v6
	v_fma_f32 v6, v26, s63, -v190
	v_exp_f32_e32 v26, v6
	v_fma_f32 v6, v27, s63, -v190
	v_exp_f32_e32 v27, v6
	v_add_f32_e32 v6, v24, v25
	v_add_f32_e32 v6, v26, v6
	v_add_f32_e32 v7, v27, v6
	v_mul_f32_e32 v6, v194, v7
	s_nop 1
	v_mov_b32_dpp v8, v6 row_ror:8 row_mask:0xf bank_mask:0xf
	v_mul_f32_e32 v6, v194, v27
	s_nop 1
	v_mov_b32_dpp v6, v6 row_ror:8 row_mask:0xf bank_mask:0xf
	v_fmac_f32_e32 v8, v194, v7
	v_mov_b32_e32 v9, v8
	s_nop 1
	v_permlane16_swap_b32_e32 v9, v8
	v_fmac_f32_e32 v6, v194, v27
	v_mov_b32_e32 v7, v6
	s_nop 1
	v_permlane16_swap_b32_e32 v7, v6
	s_and_saveexec_b64 s[86:87], s[8:9]
	s_cbranch_execz .LBB0_888
	v_add_f32_e32 v8, v8, v9
	v_add_u32_e32 v9, 0x11810, v0
	ds_add_f32 v9, v8
.LBB0_888:
	s_or_b64 exec, exec, s[86:87]
	v_fma_f32 v8, v28, s63, -v190
	v_exp_f32_e32 v28, v8
	v_fma_f32 v8, v29, s63, -v190
	v_exp_f32_e32 v29, v8
	v_fma_f32 v8, v30, s63, -v190
	v_exp_f32_e32 v30, v8
	v_fma_f32 v8, v31, s63, -v190
	v_exp_f32_e32 v31, v8
	v_add_f32_e32 v8, v28, v29
	v_add_f32_e32 v8, v30, v8
	v_add_f32_e32 v9, v31, v8
	v_mul_f32_e32 v8, v194, v9
	s_nop 1
	v_mov_b32_dpp v10, v8 row_ror:8 row_mask:0xf bank_mask:0xf
	v_mul_f32_e32 v8, v194, v31
	s_nop 1
	v_mov_b32_dpp v8, v8 row_ror:8 row_mask:0xf bank_mask:0xf
	v_fmac_f32_e32 v10, v194, v9
	v_mov_b32_e32 v11, v10
	s_nop 1
	v_permlane16_swap_b32_e32 v11, v10
	v_fmac_f32_e32 v8, v194, v31
	v_mov_b32_e32 v9, v8
	s_nop 1
	v_permlane16_swap_b32_e32 v9, v8
	s_and_saveexec_b64 s[86:87], s[8:9]
	s_cbranch_execz .LBB0_890
	v_add_f32_e32 v10, v10, v11
	v_add_u32_e32 v11, 0x11818, v0
	ds_add_f32 v11, v10
.LBB0_890:
	s_or_b64 exec, exec, s[86:87]
	v_fma_f32 v10, v96, s63, -v190
	v_exp_f32_e32 v96, v10
	v_fma_f32 v10, v97, s63, -v190
	v_exp_f32_e32 v97, v10
	v_fma_f32 v10, v98, s63, -v190
	v_exp_f32_e32 v98, v10
	v_fma_f32 v10, v99, s63, -v190
	v_exp_f32_e32 v99, v10
	v_add_f32_e32 v10, v96, v97
	v_add_f32_e32 v10, v98, v10
	v_add_f32_e32 v11, v99, v10
	v_mul_f32_e32 v10, v194, v11
	s_nop 1
	v_mov_b32_dpp v12, v10 row_ror:8 row_mask:0xf bank_mask:0xf
	v_mul_f32_e32 v10, v194, v99
	s_nop 1
	v_mov_b32_dpp v10, v10 row_ror:8 row_mask:0xf bank_mask:0xf
	v_fmac_f32_e32 v12, v194, v11
	v_mov_b32_e32 v13, v12
	s_nop 1
	v_permlane16_swap_b32_e32 v13, v12
	v_fmac_f32_e32 v10, v194, v99
	v_mov_b32_e32 v11, v10
	s_nop 1
	v_permlane16_swap_b32_e32 v11, v10
	s_and_saveexec_b64 s[86:87], s[8:9]
	s_cbranch_execz .LBB0_892
	v_add_u32_e32 v14, 0x11820, v0
	v_add_f32_e32 v12, v12, v13
	ds_add_f32 v14, v12
.LBB0_892:
	s_or_b64 exec, exec, s[86:87]
	v_fma_f32 v12, v100, s63, -v190
	v_exp_f32_e32 v100, v12
	v_fma_f32 v12, v101, s63, -v190
	v_exp_f32_e32 v101, v12
	v_fma_f32 v12, v102, s63, -v190
	v_exp_f32_e32 v102, v12
	v_fma_f32 v12, v103, s63, -v190
	v_exp_f32_e32 v103, v12
	v_add_f32_e32 v12, v100, v101
	v_add_f32_e32 v12, v102, v12
	v_add_f32_e32 v13, v103, v12
	v_mul_f32_e32 v12, v194, v13
	s_nop 1
	v_mov_b32_dpp v14, v12 row_ror:8 row_mask:0xf bank_mask:0xf
	v_mul_f32_e32 v12, v194, v103
	s_nop 1
	v_mov_b32_dpp v12, v12 row_ror:8 row_mask:0xf bank_mask:0xf
	v_fmac_f32_e32 v14, v194, v13
	v_mov_b32_e32 v15, v14
	s_nop 1
	v_permlane16_swap_b32_e32 v15, v14
	v_fmac_f32_e32 v12, v194, v103
	v_mov_b32_e32 v13, v12
	s_nop 1
	v_permlane16_swap_b32_e32 v13, v12
	s_and_saveexec_b64 s[86:87], s[8:9]
	s_cbranch_execz .LBB0_894
	v_add_f32_e32 v14, v14, v15
	v_add_u32_e32 v15, 0x11828, v0
	ds_add_f32 v15, v14
; __device__ __forceinline__ unsigned cvt_pk_bf16(float lo, float hi) { unsigned r; asm volatile("v_cvt_pk_bf16_f32 %0, %1, %2" : "=v"(r) : "v"(lo), "v"(hi)); return r; }
; template <int DQK, bool STATS, bool PRE, class Src, class Mask, class Post> ...
;     ...
;                     pk[c2].x = cvt_pk_bf16(s0[8 * c2 + 0], s0[8 * c2 + 1]); pk[c2].y = cvt_pk_bf16(s0[8 * c2 + 2], s0[8 * c2 + 3]); pk[c2].z = cvt_pk_bf16(s0[8 * c2 + 4], s0[8 * c2 + 5]); pk[c2].w = cvt_pk_bf16(s0[8 * c2 + 6], s0[8 * c2 + 7]);
;                     pk[2 + c2].x = cvt_pk_bf16(s1[8 * c2 + 0], s1[8 * c2 + 1]); pk[2 + c2].y = cvt_pk_bf16(s1[8 * c2 + 2], s1[8 * c2 + 3]); pk[2 + c2].z = cvt_pk_bf16(s1[8 * c2 + 4], s1[8 * c2 + 5]); pk[2 + c2].w = cvt_pk_bf16(s1[8 * c2 + 6], s1[8 * c2 + 7]);
;     __device__ __forceinline__ void operator()(int t, const f32x16& s0, const f32x16& s1) const {
;     ...
;                 float p3 = (kb ? s1[4 * gi + 3] : s0[4 * gi + 3]);
;                 float aa = kb ? (s1[4 * gi] + s1[4 * gi + 1] + s1[4 * gi + 2] + p3) : (s0[4 * gi] + s0[4 * gi + 1] + s0[4 * gi + 2] + p3);
;                 aa *= inv_l; p3 *= inv_l;
;                 aa += __shfl_xor(aa, 8); aa += __shfl_xor(aa, 16); p3 += __shfl_xor(p3, 8); p3 += __shfl_xor(p3, 16);
;                 Bv[kb * 4 + gi] = p3;
;                 if (c < 8) { const int j = t * 16 + kb * 8 + 2 * gi + h; row[j] += aa; }
;             }
;         asm volatile("s_waitcnt lgkmcnt(0)" ::: "memory");
;         if (c < 8) {
; #pragma unroll
;             for (int e = 0; e < 8; ++e) { const int j1 = t * 16 + (e >> 2) * 8 + 2 * (e & 3) + h + 1; if (j1 < 256) row[j1] += Bv[e]; }
;         }
;         asm volatile("s_waitcnt lgkmcnt(0)" ::: "memory");
.LBB0_894:
	s_or_b64 exec, exec, s[86:87]
	v_fma_f32 v14, v104, s63, -v190
	v_exp_f32_e32 v104, v14
	v_fma_f32 v14, v105, s63, -v190
	v_exp_f32_e32 v105, v14
	v_fma_f32 v14, v106, s63, -v190
	v_exp_f32_e32 v106, v14
	v_fma_f32 v14, v107, s63, -v190
	v_exp_f32_e32 v107, v14
	v_add_f32_e32 v14, v104, v105
	v_add_f32_e32 v14, v106, v14
	v_add_f32_e32 v15, v107, v14
	v_mul_f32_e32 v14, v194, v15
	s_nop 1
	v_mov_b32_dpp v144, v14 row_ror:8 row_mask:0xf bank_mask:0xf
	v_mul_f32_e32 v14, v194, v107
	s_nop 1
	v_mov_b32_dpp v14, v14 row_ror:8 row_mask:0xf bank_mask:0xf
	v_fmac_f32_e32 v144, v194, v15
	v_mov_b32_e32 v145, v144
	s_nop 1
	v_permlane16_swap_b32_e32 v145, v144
	v_fmac_f32_e32 v14, v194, v107
	v_mov_b32_e32 v15, v14
	s_nop 1
	v_permlane16_swap_b32_e32 v15, v14
	s_and_saveexec_b64 s[86:87], s[8:9]
	s_cbranch_execz .LBB0_896
	v_add_f32_e32 v144, v144, v145
	v_add_u32_e32 v145, 0x11830, v0
	ds_add_f32 v145, v144
.LBB0_896:
	s_or_b64 exec, exec, s[86:87]
	v_fma_f32 v108, v108, s63, -v190
	v_fma_f32 v109, v109, s63, -v190
	v_exp_f32_e32 v108, v108
	v_exp_f32_e32 v109, v109
	v_fma_f32 v110, v110, s63, -v190
	v_exp_f32_e32 v110, v110
	v_fma_f32 v111, v111, s63, -v190
	v_exp_f32_e32 v111, v111
	v_add_f32_e32 v144, v108, v109
	v_add_f32_e32 v144, v110, v144
	v_add_f32_e32 v145, v111, v144
	v_mul_f32_e32 v144, v194, v145
	s_nop 1
	v_mov_b32_dpp v146, v144 row_ror:8 row_mask:0xf bank_mask:0xf
	v_mul_f32_e32 v144, v194, v111
	s_nop 1
	v_mov_b32_dpp v144, v144 row_ror:8 row_mask:0xf bank_mask:0xf
	v_fmac_f32_e32 v146, v194, v145
	v_mov_b32_e32 v147, v146
	s_nop 1
	v_permlane16_swap_b32_e32 v147, v146
	v_fmac_f32_e32 v144, v194, v111
	v_mov_b32_e32 v145, v144
	s_nop 1
	v_permlane16_swap_b32_e32 v145, v144
	s_and_saveexec_b64 s[86:87], s[8:9]
	s_cbranch_execz .LBB0_898
	v_add_f32_e32 v146, v146, v147
	v_add_u32_e32 v147, 0x11838, v0
	ds_add_f32 v147, v146
.LBB0_898:
	s_or_b64 exec, exec, s[86:87]
	s_waitcnt lgkmcnt(0)
	s_and_saveexec_b64 s[86:87], s[8:9]
	s_cbranch_execz .LBB0_915
	v_add_u32_e32 v146, -14, v213
	v_cmp_gt_u32_e32 vcc, s94, v146
	s_and_saveexec_b64 s[88:89], vcc
	s_cbranch_execz .LBB0_901
	v_add_f32_e32 v2, v2, v3
	v_add_u32_e32 v3, 0x11804, v0
	ds_add_f32 v3, v2
.LBB0_901:
	s_or_b64 exec, exec, s[88:89]
	v_add_u32_e32 v2, -12, v213
	v_cmp_gt_u32_e32 vcc, s94, v2
	s_and_saveexec_b64 s[88:89], vcc
	s_cbranch_execz .LBB0_903
	v_add_u32_e32 v3, 0x1180c, v0
	v_add_f32_e32 v2, v4, v5
	ds_add_f32 v3, v2
.LBB0_903:
	s_or_b64 exec, exec, s[88:89]
	v_add_u32_e32 v2, -10, v213
	v_cmp_gt_u32_e32 vcc, s94, v2
	s_and_saveexec_b64 s[88:89], vcc
	s_cbranch_execz .LBB0_905
	v_add_u32_e32 v3, 0x11814, v0
	v_add_f32_e32 v2, v6, v7
	ds_add_f32 v3, v2
.LBB0_905:
	s_or_b64 exec, exec, s[88:89]
	v_add_u32_e32 v2, -8, v213
	v_cmp_gt_u32_e32 vcc, s94, v2
	s_and_saveexec_b64 s[88:89], vcc
	s_cbranch_execz .LBB0_907
	v_add_u32_e32 v3, 0x1181c, v0
	v_add_f32_e32 v2, v8, v9
	ds_add_f32 v3, v2
.LBB0_907:
	s_or_b64 exec, exec, s[88:89]
	v_add_u32_e32 v2, -6, v213
	v_cmp_gt_u32_e32 vcc, s94, v2
	s_and_saveexec_b64 s[88:89], vcc
	s_cbranch_execz .LBB0_909
	v_add_u32_e32 v3, 0x11824, v0
	v_add_f32_e32 v2, v10, v11
	ds_add_f32 v3, v2
.LBB0_909:
	s_or_b64 exec, exec, s[88:89]
	v_add_u32_e32 v2, -4, v213
	v_cmp_gt_u32_e32 vcc, s94, v2
	s_and_saveexec_b64 s[88:89], vcc
	s_cbranch_execz .LBB0_911
	v_add_u32_e32 v3, 0x1182c, v0
	v_add_f32_e32 v2, v12, v13
	ds_add_f32 v3, v2
.LBB0_911:
	s_or_b64 exec, exec, s[88:89]
	v_add_u32_e32 v2, -2, v213
	v_cmp_gt_u32_e32 vcc, s94, v2
	s_and_saveexec_b64 s[88:89], vcc
	s_cbranch_execz .LBB0_913
	v_add_u32_e32 v3, 0x11834, v0
	v_add_f32_e32 v2, v14, v15
	ds_add_f32 v3, v2
.LBB0_913:
	s_or_b64 exec, exec, s[88:89]
	v_cmp_gt_u32_e32 vcc, s94, v213
	s_and_b64 exec, exec, vcc
	s_cbranch_execz .LBB0_915
	v_add_u32_e32 v0, 0x1183c, v0
	v_add_f32_e32 v2, v144, v145
	ds_add_f32 v0, v2
.LBB0_915:
	s_or_b64 exec, exec, s[86:87]
	s_waitcnt lgkmcnt(0)
	v_cvt_pk_bf16_f32 v2, v16, v17
	v_cvt_pk_bf16_f32 v3, v18, v19
	v_cvt_pk_bf16_f32 v4, v20, v21
	v_cvt_pk_bf16_f32 v5, v22, v23
	v_cvt_pk_bf16_f32 v6, v96, v97
	v_cvt_pk_bf16_f32 v7, v98, v99
	v_cvt_pk_bf16_f32 v8, v100, v101
	v_cvt_pk_bf16_f32 v9, v102, v103
	v_cvt_pk_bf16_f32 v10, v24, v25
	v_cvt_pk_bf16_f32 v11, v26, v27
	v_cvt_pk_bf16_f32 v12, v28, v29
	v_cvt_pk_bf16_f32 v13, v30, v31
	v_cvt_pk_bf16_f32 v144, v104, v105
	v_cvt_pk_bf16_f32 v145, v106, v107
	v_cvt_pk_bf16_f32 v146, v108, v109
	v_cvt_pk_bf16_f32 v147, v110, v111

; #define LAS __attribute__((address_space(3)))
; __device__ __forceinline__ f32x16 mfma32(bf16x8 a, bf16x8 b, f32x16 c) { return __builtin_amdgcn_mfma_f32_32x32x16_bf16(a, b, c, 0, 0, 0); }
; template <int DQK, bool STATS, bool PRE, class Src, class Mask, class Post> ...
;     ...
;         if (!STATS && act) {
;             const int vb = (i & 1) * VBUF;
; #pragma unroll
;             for (int g16 = 0; g16 < 4; ++g16) {
;                 const bf16x8 pf = __builtin_bit_cast(bf16x8, pk[g16]);
; #pragma unroll
;                 for (int blk = 0; blk < 4; ++blk) {
;                     const bf16x8 vf = *(const LAS bf16x8*)(lv + vb + (blk * 32 + c) * VS_ + g16 * 32 + h * 16);
;                     a.o[blk] = mfma32(vf, pf, a.o[blk]);
;                 }
;             }
;             __builtin_amdgcn_sched_group_barrier(0x100, 6, 0);
; #pragma unroll
;             for (int z = 0; z < 10; ++z) { __builtin_amdgcn_sched_group_barrier(0x008, 1, 0); __builtin_amdgcn_sched_group_barrier(0x100, 1, 0); }
;             __builtin_amdgcn_sched_group_barrier(0x008, 6, 0);
;         }
.LBB0_933:
	s_or_b64 exec, exec, s[38:39]
	s_and_saveexec_b64 s[38:39], s[22:23]
	s_cbranch_execz .LBB0_936
	s_bitcmp1_b32 s50, 0
	s_cselect_b32 s22, 0x4800, 0
	v_add_u32_e32 v0, s22, v211
	ds_read_b128 v[214:217], v0 offset:34816
	ds_read_b128 v[218:221], v0 offset:39424
	ds_read_b128 v[222:225], v0 offset:44032
	ds_read_b128 v[226:229], v0 offset:48640
	ds_read_b128 v[230:233], v0 offset:34848
	ds_read_b128 v[234:237], v0 offset:39456
	ds_read_b128 v[238:241], v0 offset:44064
	ds_read_b128 v[242:245], v0 offset:48672
	s_waitcnt lgkmcnt(7)
	v_mfma_f32_32x32x16_bf16 v[80:95], v[214:217], v[2:5], v[80:95]
	ds_read_b128 v[214:217], v0 offset:34880
	s_waitcnt lgkmcnt(7)
	v_mfma_f32_32x32x16_bf16 v[64:79], v[218:221], v[2:5], v[64:79]
	ds_read_b128 v[218:221], v0 offset:39488
	s_waitcnt lgkmcnt(7)
	v_mfma_f32_32x32x16_bf16 v[48:63], v[222:225], v[2:5], v[48:63]
	ds_read_b128 v[222:225], v0 offset:44096
	s_waitcnt lgkmcnt(7)
	v_mfma_f32_32x32x16_bf16 v[32:47], v[226:229], v[2:5], v[32:47]
	ds_read_b128 v[226:229], v0 offset:48704
	s_waitcnt lgkmcnt(7)
	v_mfma_f32_32x32x16_bf16 v[80:95], v[230:233], v[10:13], v[80:95]
	ds_read_b128 v[230:233], v0 offset:34912
	s_waitcnt lgkmcnt(7)
	v_mfma_f32_32x32x16_bf16 v[64:79], v[234:237], v[10:13], v[64:79]
	ds_read_b128 v[234:237], v0 offset:39520
	s_waitcnt lgkmcnt(7)
	v_mfma_f32_32x32x16_bf16 v[48:63], v[238:241], v[10:13], v[48:63]
	ds_read_b128 v[238:241], v0 offset:44128
	s_waitcnt lgkmcnt(7)
	v_mfma_f32_32x32x16_bf16 v[32:47], v[242:245], v[10:13], v[32:47]
	ds_read_b128 v[242:245], v0 offset:48736
	s_waitcnt lgkmcnt(7)
	v_mfma_f32_32x32x16_bf16 v[80:95], v[214:217], v[6:9], v[80:95]
	s_waitcnt lgkmcnt(6)
	v_mfma_f32_32x32x16_bf16 v[64:79], v[218:221], v[6:9], v[64:79]
	s_waitcnt lgkmcnt(5)
	v_mfma_f32_32x32x16_bf16 v[48:63], v[222:225], v[6:9], v[48:63]
	s_waitcnt lgkmcnt(4)
	v_mfma_f32_32x32x16_bf16 v[32:47], v[226:229], v[6:9], v[32:47]
	s_waitcnt lgkmcnt(3)
	v_mfma_f32_32x32x16_bf16 v[80:95], v[230:233], v[144:147], v[80:95]
	s_waitcnt lgkmcnt(2)
	v_mfma_f32_32x32x16_bf16 v[64:79], v[234:237], v[144:147], v[64:79]
	s_waitcnt lgkmcnt(1)
	v_mfma_f32_32x32x16_bf16 v[48:63], v[238:241], v[144:147], v[48:63]
	s_waitcnt lgkmcnt(0)
	v_mfma_f32_32x32x16_bf16 v[32:47], v[242:245], v[144:147], v[32:47]
	s_or_b64 exec, exec, s[38:39]
	s_cmp_ge_u32 s50, s36
	s_mov_b64 s[22:23], 0
	s_cbranch_scc0 .LBB0_937

;     __device__ __forceinline__ bool begin(int t) { kb_ = t * 64; on = (selw[t >> 5] >> (t & 31)) & 1u; return __ballot(on) != 0ull; }
; template <int DQK, bool STATS, bool PRE, class Src, class Mask, class Post> ...
;     ...
;         if (t + 1 < te) { actn = mask.begin(t + 1); if (actn) { if ((i + 1) & 1) ATT_QK(1); else ATT_QK(0); } }
.LBB0_937:
	v_cmp_le_i32_e32 vcc, s93, v153
	s_and_saveexec_b64 s[38:39], vcc
	s_cbranch_execz .LBB0_943
	s_bitcmp0_b32 s50, 0
	s_mov_b64 s[22:23], -1
	s_cbranch_scc1 .LBB0_940
	s_mov_b64 s[22:23], 0
	ds_read_b128 v[214:217], v212
	ds_read_b128 v[218:221], v212 offset:8704
	ds_read_b128 v[222:225], v212 offset:32
	ds_read_b128 v[226:229], v212 offset:8736
	ds_read_b128 v[230:233], v212 offset:64
	ds_read_b128 v[234:237], v212 offset:8768
	ds_read_b128 v[238:241], v212 offset:96
	ds_read_b128 v[242:245], v212 offset:8800
	s_waitcnt lgkmcnt(7)
	v_mfma_f32_32x32x16_bf16 v[16:31], v[214:217], v[112:115], 0
	ds_read_b128 v[214:217], v212 offset:128
	s_waitcnt lgkmcnt(7)
	v_mfma_f32_32x32x16_bf16 v[96:111], v[218:221], v[112:115], 0
	ds_read_b128 v[218:221], v212 offset:8832
	s_waitcnt lgkmcnt(7)
	v_mfma_f32_32x32x16_bf16 v[16:31], v[222:225], v[116:119], v[16:31]
	ds_read_b128 v[222:225], v212 offset:160
	s_waitcnt lgkmcnt(7)
	v_mfma_f32_32x32x16_bf16 v[96:111], v[226:229], v[116:119], v[96:111]
	ds_read_b128 v[226:229], v212 offset:8864
	s_waitcnt lgkmcnt(7)
	v_mfma_f32_32x32x16_bf16 v[16:31], v[230:233], v[120:123], v[16:31]
	ds_read_b128 v[230:233], v212 offset:192
	s_waitcnt lgkmcnt(7)
	v_mfma_f32_32x32x16_bf16 v[96:111], v[234:237], v[120:123], v[96:111]
	ds_read_b128 v[234:237], v212 offset:8896
	s_waitcnt lgkmcnt(7)
	v_mfma_f32_32x32x16_bf16 v[16:31], v[238:241], v[124:127], v[16:31]
	ds_read_b128 v[238:241], v212 offset:224
	s_waitcnt lgkmcnt(7)
	v_mfma_f32_32x32x16_bf16 v[96:111], v[242:245], v[124:127], v[96:111]
	ds_read_b128 v[242:245], v212 offset:8928
	s_waitcnt lgkmcnt(7)
	v_mfma_f32_32x32x16_bf16 v[16:31], v[214:217], v[128:131], v[16:31]
	s_waitcnt lgkmcnt(6)
	v_mfma_f32_32x32x16_bf16 v[96:111], v[218:221], v[128:131], v[96:111]
	s_waitcnt lgkmcnt(5)
	v_mfma_f32_32x32x16_bf16 v[16:31], v[222:225], v[132:135], v[16:31]
	s_waitcnt lgkmcnt(4)
	v_mfma_f32_32x32x16_bf16 v[96:111], v[226:229], v[132:135], v[96:111]
	s_waitcnt lgkmcnt(3)
	v_mfma_f32_32x32x16_bf16 v[16:31], v[230:233], v[136:139], v[16:31]
	s_waitcnt lgkmcnt(2)
	v_mfma_f32_32x32x16_bf16 v[96:111], v[234:237], v[136:139], v[96:111]
	s_waitcnt lgkmcnt(1)
	v_mfma_f32_32x32x16_bf16 v[16:31], v[238:241], v[140:143], v[16:31]
	s_waitcnt lgkmcnt(0)
	v_mfma_f32_32x32x16_bf16 v[96:111], v[242:245], v[140:143], v[96:111]
.LBB0_940:
	s_andn2_b64 vcc, exec, s[22:23]
	s_cbranch_vccnz .LBB0_942
	ds_read_b128 v[214:217], v212 offset:17408
	ds_read_b128 v[218:221], v212 offset:26112
	ds_read_b128 v[222:225], v212 offset:17440
	ds_read_b128 v[226:229], v212 offset:26144
	ds_read_b128 v[230:233], v212 offset:17472
	ds_read_b128 v[234:237], v212 offset:26176
	ds_read_b128 v[238:241], v212 offset:17504
	ds_read_b128 v[242:245], v212 offset:26208
	s_waitcnt lgkmcnt(7)
	v_mfma_f32_32x32x16_bf16 v[16:31], v[214:217], v[112:115], 0
	ds_read_b128 v[214:217], v212 offset:17536
	s_waitcnt lgkmcnt(7)
	v_mfma_f32_32x32x16_bf16 v[96:111], v[218:221], v[112:115], 0
	ds_read_b128 v[218:221], v212 offset:26240
	s_waitcnt lgkmcnt(7)
	v_mfma_f32_32x32x16_bf16 v[16:31], v[222:225], v[116:119], v[16:31]
	ds_read_b128 v[222:225], v212 offset:17568
	s_waitcnt lgkmcnt(7)
	v_mfma_f32_32x32x16_bf16 v[96:111], v[226:229], v[116:119], v[96:111]
	ds_read_b128 v[226:229], v212 offset:26272
	s_waitcnt lgkmcnt(7)
	v_mfma_f32_32x32x16_bf16 v[16:31], v[230:233], v[120:123], v[16:31]
	ds_read_b128 v[230:233], v212 offset:17600
	s_waitcnt lgkmcnt(7)
	v_mfma_f32_32x32x16_bf16 v[96:111], v[234:237], v[120:123], v[96:111]
	ds_read_b128 v[234:237], v212 offset:26304
	s_waitcnt lgkmcnt(7)
	v_mfma_f32_32x32x16_bf16 v[16:31], v[238:241], v[124:127], v[16:31]
	ds_read_b128 v[238:241], v212 offset:17632
	s_waitcnt lgkmcnt(7)
	v_mfma_f32_32x32x16_bf16 v[96:111], v[242:245], v[124:127], v[96:111]
	ds_read_b128 v[242:245], v212 offset:26336
	s_waitcnt lgkmcnt(7)
	v_mfma_f32_32x32x16_bf16 v[16:31], v[214:217], v[128:131], v[16:31]
	s_waitcnt lgkmcnt(6)
	v_mfma_f32_32x32x16_bf16 v[96:111], v[218:221], v[128:131], v[96:111]
	s_waitcnt lgkmcnt(5)
	v_mfma_f32_32x32x16_bf16 v[16:31], v[222:225], v[132:135], v[16:31]
	s_waitcnt lgkmcnt(4)
	v_mfma_f32_32x32x16_bf16 v[96:111], v[226:229], v[132:135], v[96:111]
	s_waitcnt lgkmcnt(3)
	v_mfma_f32_32x32x16_bf16 v[16:31], v[230:233], v[136:139], v[16:31]
	s_waitcnt lgkmcnt(2)
	v_mfma_f32_32x32x16_bf16 v[96:111], v[234:237], v[136:139], v[96:111]
	s_waitcnt lgkmcnt(1)
	v_mfma_f32_32x32x16_bf16 v[16:31], v[238:241], v[140:143], v[16:31]
	s_waitcnt lgkmcnt(0)
	v_mfma_f32_32x32x16_bf16 v[96:111], v[242:245], v[140:143], v[96:111]
